# v024fold
# speedup vs baseline: 1.0610x; 1.0029x over previous
; DEV int opaque_tid() { int t = threadIdx.x & 255; asm volatile("" : "+v"(t)); return t; }
; __device__ void fold_job(const float* win_l, HALF* WinT, int job, float* smf) {
;   const int tid = opaque_tid();
;   const int k = job >> 3, nb = job & 7;
;   const int np = nb * 256 + tid;
;   const int isS = nb >> 2, g = nb & 3, t = tid;
;   __syncthreads();
;   {
;     float sn, cs;
;     sincospif((float)tid * 0.0078125f, &sn, &cs);
;     smf[tid] = cs;
;     smf[256 + tid] = sn;
;     smf[512 + tid] = win_l[(size_t)k * 13312 + g * 256 + tid];
;   }
;   __syncthreads();
;   const float* wrow = smf + 512;
;   const float* tab = smf + isS * 256;
;   float acc = 0.f;
; #pragma unroll 8
;   for (int c = 0; c < 256; ++c) acc += wrow[c] * tab[(c * t) & 255];
;   acc *= isS ? -0.0625f : 0.0625f;
;   WinT[(size_t)np * 1024 + k] = (HALF)acc;
.LBB0_85:
	s_andn2_b64 vcc, exec, s[12:13]
	s_cbranch_vccnz .LBB0_54
	s_ashr_i32 s76, s17, 3
	s_and_b32 s12, s17, 7
	s_ashr_i32 s77, s76, 31
	s_lshl_b32 s18, s17, 8
	s_mul_i32 vcc_lo, s76, 0xd000
	s_mul_hi_i32 s13, s76, 0xd000
	s_add_u32 vcc_lo, s2, vcc_lo
	s_addc_u32 s13, s3, s13
	s_lshl_b32 s17, s17, 10
	s_and_b32 s17, s17, 0xc00
	v_mov_b32_e32 v0, v182
	s_add_u32 vcc_lo, vcc_lo, s17
	s_addc_u32 vcc_hi, s13, 0
	v_ashrrev_i32_e32 v1, 31, v0
	v_lshl_add_u64 v[2:3], v[0:1], 2, vcc
	s_waitcnt lgkmcnt(0)
	s_barrier
	global_load_dword v9, v[2:3], off
	v_cvt_f32_i32_e32 v10, v0
	v_lshlrev_b32_e32 v2, 2, v0
	v_readlane_b32 s4, v255, 34
	s_and_b32 s17, s18, 0x400
	v_mul_f32_e32 v10, 0x3c000000, v10
	v_mul_f32_e64 v13, |v10|, 0.5
	v_add_u32_e32 v11, s4, v2
	s_add_i32 s17, s4, s17
	v_fract_f32_e32 v14, v13
	s_mov_b32 s4, 0x7f800000
	v_add_f32_e32 v14, v14, v14
	v_cmp_neq_f32_e32 vcc, s4, v13
	v_mov_b32_e32 v16, 0xbf1f24be
	v_mov_b32_e32 v18, 0x3e642e9d
	v_cndmask_b32_e32 v13, 0, v14, vcc
	v_cmp_gt_f32_e64 vcc, |v10|, 1.0
	v_and_b32_e32 v12, 0x7fffffff, v10
	v_xor_b32_e32 v12, v12, v10
	v_cndmask_b32_e64 v13, |v10|, v13, vcc
	v_add_f32_e32 v14, v13, v13
	v_rndne_f32_e32 v14, v14
	v_fmac_f32_e32 v13, -0.5, v14
	v_mul_f32_e32 v15, v13, v13
	v_cvt_i32_f32_e32 v14, v14
	v_fmamk_f32 v16, v15, 0x3e75aa41, v16
	v_fmamk_f32 v18, v15, 0x3d4be544, v18
	v_fmaak_f32 v16, v15, v16, 0x40234736
	v_mul_f32_e32 v17, v13, v15
	v_fmaak_f32 v18, v15, v18, 0xbfaad1da
	v_fmaak_f32 v16, v15, v16, 0xc0a55e0e
	v_fmaak_f32 v18, v15, v18, 0x4081e0d3
	v_mul_f32_e32 v16, v17, v16
	v_lshlrev_b32_e32 v19, 30, v14
	v_and_b32_e32 v14, 1, v14
	v_fmaak_f32 v17, v15, v18, 0xc09de9e6
	v_fmac_f32_e32 v16, 0x40490fdb, v13
	v_fma_f32 v13, v15, v17, 1.0
	v_cmp_eq_u32_e32 vcc, 0, v14
	v_xor_b32_e32 v15, 0x80000000, v16
	s_brev_b32 s18, 1
	v_cndmask_b32_e32 v14, v13, v16, vcc
	v_cndmask_b32_e32 v13, v15, v13, vcc
	v_and_b32_e32 v18, 0x80000000, v19
	v_xor_b32_e32 v12, v12, v14
	v_bitop3_b32 v13, v13, v19, s18 bitop3:0x78
	s_movk_i32 s18, 0x1f8
	v_xor_b32_e32 v12, v12, v18
	v_cmp_class_f32_e64 vcc, v10, s18
	v_mov_b32_e32 v14, 0x7fc00000
	v_mov_b32_e32 v1, 0
	v_cndmask_b32_e32 v10, v14, v13, vcc
	v_cndmask_b32_e32 v12, v14, v12, vcc
	s_mov_b32 s13, 0
	v_lshlrev_b32_e32 v3, 3, v0
	v_lshlrev_b32_e32 v4, 1, v0
	v_lshl_add_u32 v5, v0, 1, v0
	v_lshl_add_u32 v6, v0, 2, v0
	v_mul_lo_u32 v7, v0, 6
	v_mul_lo_u32 v8, v0, 7
	v_readlane_b32 s4, v255, 35
	ds_write2st64_b32 v11, v10, v12 offset1:4
	s_waitcnt vmcnt(0)
	ds_write_b32 v11, v9 offset:2048
	v_mov_b32_e32 v9, 0
	s_waitcnt lgkmcnt(0)
	s_barrier
	s_movk_i32 s18, 0x3fc
	v_mov_b32_e32 v38, s17
	v_mov_b32_e32 v39, s4
	v_lshlrev_b32_e32 v26, 5, v0
	v_mov_b32_e32 v30, v38
	v_lshlrev_b32_e32 v27, 2, v0
	v_bfi_b32 v31, s18, v27, v38
	v_lshlrev_b32_e32 v27, 2, v4
	v_bfi_b32 v32, s18, v27, v38
	v_lshlrev_b32_e32 v27, 2, v5
	v_bfi_b32 v33, s18, v27, v38
	v_lshlrev_b32_e32 v27, 2, v2
	v_bfi_b32 v34, s18, v27, v38
	v_lshlrev_b32_e32 v27, 2, v6
	v_bfi_b32 v35, s18, v27, v38
	v_lshlrev_b32_e32 v27, 2, v7
	v_bfi_b32 v36, s18, v27, v38
	v_lshlrev_b32_e32 v27, 2, v8
	v_bfi_b32 v37, s18, v27, v38
	ds_read_b128 v[10:13], v39
	ds_read_b128 v[14:17], v39 offset:16
	ds_read_b32 v18, v30
	ds_read_b32 v19, v31
	ds_read_b32 v20, v32
	ds_read_b32 v21, v33
	ds_read_b32 v22, v34
	ds_read_b32 v23, v35
	ds_read_b32 v24, v36
	ds_read_b32 v25, v37
	v_add_u32_e32 v27, v30, v26
	v_bfi_b32 v30, s18, v27, v38
	v_add_u32_e32 v27, v31, v26
	v_bfi_b32 v31, s18, v27, v38
	v_add_u32_e32 v27, v32, v26
	v_bfi_b32 v32, s18, v27, v38
	v_add_u32_e32 v27, v33, v26
	v_bfi_b32 v33, s18, v27, v38
	v_add_u32_e32 v27, v34, v26
	v_bfi_b32 v34, s18, v27, v38
	v_add_u32_e32 v27, v35, v26
	v_bfi_b32 v35, s18, v27, v38
	v_add_u32_e32 v27, v36, v26
	v_bfi_b32 v36, s18, v27, v38
	v_add_u32_e32 v27, v37, v26
	v_bfi_b32 v37, s18, v27, v38
	s_mov_b32 s13, 0
.Lfold_loop:
	ds_read_b128 v[40:43], v39 offset:32
	ds_read_b128 v[44:47], v39 offset:48
	ds_read_b32 v48, v30
	ds_read_b32 v49, v31
	ds_read_b32 v50, v32
	ds_read_b32 v51, v33
	ds_read_b32 v52, v34
	ds_read_b32 v53, v35
	ds_read_b32 v54, v36
	ds_read_b32 v55, v37
	v_add_u32_e32 v27, v30, v26
	v_bfi_b32 v30, s18, v27, v38
	v_add_u32_e32 v27, v31, v26
	v_bfi_b32 v31, s18, v27, v38
	v_add_u32_e32 v27, v32, v26
	v_bfi_b32 v32, s18, v27, v38
	v_add_u32_e32 v27, v33, v26
	v_bfi_b32 v33, s18, v27, v38
	v_add_u32_e32 v27, v34, v26
	v_bfi_b32 v34, s18, v27, v38
	v_add_u32_e32 v27, v35, v26
	v_bfi_b32 v35, s18, v27, v38
	v_add_u32_e32 v27, v36, v26
	v_bfi_b32 v36, s18, v27, v38
	v_add_u32_e32 v27, v37, v26
	v_bfi_b32 v37, s18, v27, v38
	s_waitcnt lgkmcnt(10)
	v_fmac_f32_e32 v9, v10, v18
	v_fmac_f32_e32 v9, v11, v19
	v_fmac_f32_e32 v9, v12, v20
	v_fmac_f32_e32 v9, v13, v21
	v_fmac_f32_e32 v9, v14, v22
	v_fmac_f32_e32 v9, v15, v23
	v_fmac_f32_e32 v9, v16, v24
	v_fmac_f32_e32 v9, v17, v25
	v_add_u32_e32 v39, 64, v39
	ds_read_b128 v[10:13], v39
	ds_read_b128 v[14:17], v39 offset:16
	ds_read_b32 v18, v30
	ds_read_b32 v19, v31
	ds_read_b32 v20, v32
	ds_read_b32 v21, v33
	ds_read_b32 v22, v34
	ds_read_b32 v23, v35
	ds_read_b32 v24, v36
	ds_read_b32 v25, v37
	v_add_u32_e32 v27, v30, v26
	v_bfi_b32 v30, s18, v27, v38
	v_add_u32_e32 v27, v31, v26
	v_bfi_b32 v31, s18, v27, v38
	v_add_u32_e32 v27, v32, v26
	v_bfi_b32 v32, s18, v27, v38
	v_add_u32_e32 v27, v33, v26
	v_bfi_b32 v33, s18, v27, v38
	v_add_u32_e32 v27, v34, v26
	v_bfi_b32 v34, s18, v27, v38
	v_add_u32_e32 v27, v35, v26
	v_bfi_b32 v35, s18, v27, v38
	v_add_u32_e32 v27, v36, v26
	v_bfi_b32 v36, s18, v27, v38
	v_add_u32_e32 v27, v37, v26
	v_bfi_b32 v37, s18, v27, v38
	s_waitcnt lgkmcnt(10)
	v_fmac_f32_e32 v9, v40, v48
	v_fmac_f32_e32 v9, v41, v49
	v_fmac_f32_e32 v9, v42, v50
	v_fmac_f32_e32 v9, v43, v51
	v_fmac_f32_e32 v9, v44, v52
	v_fmac_f32_e32 v9, v45, v53
	v_fmac_f32_e32 v9, v46, v54
	v_fmac_f32_e32 v9, v47, v55
	s_add_i32 s13, s13, 1
	s_cmp_lg_u32 s13, 16
	s_cbranch_scc1 .Lfold_loop
	s_cmp_lt_u32 s12, 4
	s_cselect_b64 vcc, -1, 0
	v_mov_b32_e32 v1, 0x3d800000
	v_mov_b32_e32 v2, 0xbd800000
	v_lshl_add_u32 v0, s12, 8, v0
	v_cndmask_b32_e32 v1, v2, v1, vcc
	v_fma_mixlo_f16 v2, v1, v9, 0
	v_ashrrev_i32_e32 v1, 31, v0
	v_lshlrev_b64 v[0:1], 11, v[0:1]
	v_lshl_add_u64 v[0:1], s[0:1], 0, v[0:1]
	v_lshl_add_u64 v[0:1], s[76:77], 1, v[0:1]
	flat_store_short v[0:1], v2
	s_branch .LBB0_54
